# attention tile loops: redundant second scalar compare at the loop head dropped (branch on the first compare's SCC)
# speedup vs baseline: 1.0030x; 1.0030x over previous
.LBB0_580:
	s_cmp_lt_i32 s65, s47
	s_cselect_b64 s[50:51], -1, 0
	s_cbranch_scc0 .LBB0_584
	s_and_b32 s10, s65, 1
	s_mul_i32 s11, s10, 0x3000
	s_add_i32 s11, s11, s99
	s_mov_b32 m0, s11
	s_nop 0
	global_load_lds_dwordx4 v[184:185], off
	s_cmp_lg_u64 s[4:5], 0
	s_cbranch_scc0 .LBB0_583
	s_add_i32 m0, s11, 0x2000
	s_nop 0
	global_load_lds_dwordx4 v[186:187], off

.LBB0_612:
	s_cmp_lt_i32 s63, s50
	s_cselect_b64 s[48:49], -1, 0
	s_cbranch_scc0 .LBB0_616
	s_and_b32 s10, s63, 1
	s_mul_i32 s11, s10, 0x3000
	s_add_i32 s11, s11, s99
	s_mov_b32 m0, s11
	s_nop 0
	global_load_lds_dwordx4 v[174:175], off
	s_cmp_lg_u64 s[4:5], 0
	s_cbranch_scc0 .LBB0_615
	s_add_i32 m0, s11, 0x2000
	s_nop 0
	global_load_lds_dwordx4 v[172:173], off
